# fix: 2 wait states restored between v_cvt_pk and the PV MFMA in NA (had been shortened to 1); NA K/V waits moved to the register-copy point
# speedup vs baseline: 1.0553x; 1.0010x over previous
; __device__ __forceinline__ void na_item(const bf16_t* __restrict__ proj, const bf16_t* __restrict__ projT, bf16_t* aout, const float* __restrict__ relb  , int item, int seqlen, LAS unsigned char* lds, int w, int lane) {
;     ...
;     for (int t = 0; t < 16; ++t) {
;         if (t + 1 < 16) na_load(nxt, proj, projT, ktok0 + 32 * (t + 1), h, c, hh);
;     ...
;         cur = nxt;
.LBB0_352:
	s_waitcnt vmcnt(0)
	v_mov_b64_e32 v[148:149], v[144:145]
	v_mov_b64_e32 v[152:153], v[140:141]
	v_mov_b64_e32 v[156:157], v[136:137]
	v_mov_b64_e32 v[160:161], v[132:133]
	v_mov_b64_e32 v[116:117], v[188:189]
	v_mov_b64_e32 v[114:115], v[186:187]
	v_mov_b64_e32 v[124:125], v[184:185]
	v_mov_b64_e32 v[122:123], v[182:183]
	v_mov_b64_e32 v[120:121], v[180:181]
	v_mov_b64_e32 v[118:119], v[178:179]
	v_mov_b64_e32 v[128:129], v[176:177]
	v_mov_b64_e32 v[126:127], v[174:175]
	v_mov_b64_e32 v[146:147], v[142:143]
	v_mov_b64_e32 v[150:151], v[138:139]
	v_mov_b64_e32 v[154:155], v[134:135]
	v_mov_b64_e32 v[158:159], v[130:131]
	s_cmpk_eq_i32 s28, 0x1e0
	s_cbranch_scc1 .LBB0_354

; __device__ __forceinline__ f32x16 mfma32(bf16x8 a, bf16x8 b, f32x16 c) { return __builtin_amdgcn_mfma_f32_32x32x16_bf16(a, b, c, 0, 0, 0); }
; __device__ __forceinline__ f32x16 zero16() { return (f32x16){0.f, 0.f, 0.f, 0.f, 0.f, 0.f, 0.f, 0.f, 0.f, 0.f, 0.f, 0.f, 0.f, 0.f, 0.f, 0.f}; }
; __device__ __forceinline__ float xhalf_max(float x) { const auto rr = __builtin_amdgcn_permlane32_swap(__float_as_uint(x), __float_as_uint(x), false, false); return fmaxf(__uint_as_float(rr[0]), __uint_as_float(rr[1])); }
; __device__ __forceinline__ void na_item(const bf16_t* __restrict__ proj, const bf16_t* __restrict__ projT, bf16_t* aout, const float* __restrict__ relb  , int item, int seqlen, LAS unsigned char* lds, int w, int lane) {
;     ...
;         for (int qh = 0; qh < 2; ++qh) {
;             f32x16 x = zero16();
; #pragma unroll
;             for (int s = 0; s < 4; ++s) x = mfma32(cur.k[s], qf[qh][s], x);
;             const int qc = 32 * qh + c; float mt = -1e30f;
; #pragma unroll
;             for (int rg = 0; rg < 16; ++rg) { const int kc = 32 * chalf + (rg & 3) + 8 * (rg >> 2) + 4 * hh;
;                 const bool valid = (kc >= cs[qh]) && (kc < cs[qh] + 16);
;                 const float sv = fmaf(x[rg], 0.18033688011112042f, bias[brow + kc - qc + 15]) + (valid ? 0.f : -__builtin_inff());
;                 x[rg] = sv; mt = fmaxf(mt, sv); }
;             mt = xhalf_max(mt);
;             if (__builtin_amdgcn_ballot_w64(mt > mrun[qh] + 8.0f) != 0ull) {
;                 const float mnew = fmaxf(mrun[qh], mt), alpha = __builtin_amdgcn_exp2f(mrun[qh] - mnew);
;                 mrun[qh] = mnew; lrun[qh] *= alpha; O[qh][0] *= alpha; O[qh][1] *= alpha; }
.LBB0_354:
	s_waitcnt vmcnt(8)
	v_mfma_f32_32x32x16_bf16 v[66:81], v[158:161], v[82:85], 0
	s_lshr_b32 s0, s29, 1
	s_add_i32 s10, s7, s0
	s_mul_i32 s10, s10, 31
	v_and_or_b32 v0, s28, 32, v196
	v_sub_u32_e32 v220, s10, v190
	v_lshlrev_b32_e32 v220, 2, v220
	v_lshlrev_b32_e32 v209, 2, v0
	v_mfma_f32_32x32x16_bf16 v[66:81], v[154:157], v[86:89], v[66:81]
	v_add3_u32 v219, s27, v220, v209
	v_add_u32_e32 v219, 0x4a0, v219
	v_sub_u32_e32 v218, v0, v192
	ds_read2_b32 v[210:211], v219 offset1:1
	ds_read2_b32 v[212:213], v219 offset0:2 offset1:3
	ds_read2_b32 v[214:215], v219 offset0:4 offset1:5
	ds_read2_b32 v[216:217], v219 offset0:6 offset1:7
	v_mfma_f32_32x32x16_bf16 v[66:81], v[150:153], v[90:93], v[66:81]
	ds_read2_b32 v[222:223], v219 offset0:16 offset1:17
	ds_read2_b32 v[224:225], v219 offset0:18 offset1:19
	ds_read2_b32 v[226:227], v219 offset0:20 offset1:21
	ds_read2_b32 v[228:229], v219 offset0:22 offset1:23
	v_mfma_f32_32x32x16_bf16 v[66:81], v[146:149], v[94:97], v[66:81]
	s_waitcnt lgkmcnt(0)
	s_nop 11
	v_fmac_f32_e32 v210, 0x3e38aa3b, v66
	v_fmac_f32_e32 v211, 0x3e38aa3b, v67
	v_fmac_f32_e32 v212, 0x3e38aa3b, v68
	v_fmac_f32_e32 v213, 0x3e38aa3b, v69
	v_fmac_f32_e32 v214, 0x3e38aa3b, v70
	v_fmac_f32_e32 v215, 0x3e38aa3b, v71
	v_fmac_f32_e32 v216, 0x3e38aa3b, v72
	v_fmac_f32_e32 v217, 0x3e38aa3b, v73
	v_fmac_f32_e32 v222, 0x3e38aa3b, v74
	v_fmac_f32_e32 v223, 0x3e38aa3b, v75
	v_fmac_f32_e32 v224, 0x3e38aa3b, v76
	v_fmac_f32_e32 v225, 0x3e38aa3b, v77
	v_fmac_f32_e32 v226, 0x3e38aa3b, v78
	v_fmac_f32_e32 v227, 0x3e38aa3b, v79
	v_fmac_f32_e32 v228, 0x3e38aa3b, v80
	v_fmac_f32_e32 v229, 0x3e38aa3b, v81
	v_add_u32_e32 v230, 1, v218
	v_add_u32_e32 v231, 2, v218
	v_add_u32_e32 v233, 3, v218
	v_cmp_gt_u32_e32 vcc, 16, v218
	v_cmp_gt_u32_e64 s[0:1], 16, v230
	v_cmp_gt_u32_e64 s[38:39], 16, v231
	v_cmp_gt_u32_e64 s[40:41], 16, v233
	v_cndmask_b32_e32 v66, v241, v210, vcc
	v_cndmask_b32_e64 v67, v241, v211, s[0:1]
	v_cndmask_b32_e64 v68, v241, v212, s[38:39]
	v_cndmask_b32_e64 v69, v241, v213, s[40:41]
	v_add_u32_e32 v220, 4, v218
	v_add_u32_e32 v230, 5, v218
	v_add_u32_e32 v231, 6, v218
	v_add_u32_e32 v233, 7, v218
	v_cmp_gt_u32_e32 vcc, 16, v220
	v_cmp_gt_u32_e64 s[0:1], 16, v230
	v_cmp_gt_u32_e64 s[38:39], 16, v231
	v_cmp_gt_u32_e64 s[40:41], 16, v233
	v_cndmask_b32_e32 v70, v241, v214, vcc
	v_cndmask_b32_e64 v71, v241, v215, s[0:1]
	v_cndmask_b32_e64 v72, v241, v216, s[38:39]
	v_cndmask_b32_e64 v73, v241, v217, s[40:41]
	v_add_u32_e32 v220, 16, v218
	v_add_u32_e32 v230, 17, v218
	v_add_u32_e32 v231, 18, v218
	v_add_u32_e32 v233, 19, v218
	v_cmp_gt_u32_e32 vcc, 16, v220
	v_cmp_gt_u32_e64 s[0:1], 16, v230
	v_cmp_gt_u32_e64 s[38:39], 16, v231
	v_cmp_gt_u32_e64 s[40:41], 16, v233
	v_cndmask_b32_e32 v74, v241, v222, vcc
	v_cndmask_b32_e64 v75, v241, v223, s[0:1]
	v_cndmask_b32_e64 v76, v241, v224, s[38:39]
	v_cndmask_b32_e64 v77, v241, v225, s[40:41]
	v_add_u32_e32 v220, 20, v218
	v_add_u32_e32 v230, 21, v218
	v_add_u32_e32 v231, 22, v218
	v_add_u32_e32 v233, 23, v218
	v_cmp_gt_u32_e32 vcc, 16, v220
	v_cmp_gt_u32_e64 s[0:1], 16, v230
	v_cmp_gt_u32_e64 s[38:39], 16, v231
	v_cmp_gt_u32_e64 s[40:41], 16, v233
	v_cndmask_b32_e32 v78, v241, v226, vcc
	v_cndmask_b32_e64 v79, v241, v227, s[0:1]
	v_cndmask_b32_e64 v80, v241, v228, s[38:39]
	v_cndmask_b32_e64 v81, v241, v229, s[40:41]
	v_max3_f32 v221, v66, s19, v67
	v_max3_f32 v221, v221, v68, v69
	v_max3_f32 v221, v221, v70, v71
	v_max3_f32 v221, v221, v72, v73
	v_max3_f32 v221, v221, v74, v75
	v_max3_f32 v221, v221, v76, v77
	v_max3_f32 v221, v221, v78, v79
	v_max3_f32 v221, v221, v80, v81
	v_mov_b32_e32 v222, v221
	s_nop 1
	v_permlane32_swap_b32_e32 v221, v222
	v_max_f32_e32 v222, v222, v222
	v_max_f32_e32 v221, v221, v221
	v_max_f32_e32 v221, v221, v222
	v_add_f32_e32 v222, 0x41000000, v208
	v_cmp_gt_f32_e32 vcc, v221, v222
	s_cbranch_vccz .LBB0_356
	v_max_f32_e32 v221, v221, v221
	v_max_f32_e32 v222, v208, v208
	v_max_f32_e32 v221, v222, v221
	v_sub_f32_e32 v208, v208, v221
	v_exp_f32_e32 v208, v208
	s_nop 0
	v_mul_f32_e32 v206, v206, v208
	v_pk_mul_f32 v[64:65], v[64:65], v[208:209] op_sel_hi:[1,0]
	v_pk_mul_f32 v[62:63], v[62:63], v[208:209] op_sel_hi:[1,0]
	v_pk_mul_f32 v[60:61], v[60:61], v[208:209] op_sel_hi:[1,0]
	v_pk_mul_f32 v[58:59], v[58:59], v[208:209] op_sel_hi:[1,0]
	v_pk_mul_f32 v[56:57], v[56:57], v[208:209] op_sel_hi:[1,0]
	v_pk_mul_f32 v[54:55], v[54:55], v[208:209] op_sel_hi:[1,0]
	v_pk_mul_f32 v[52:53], v[52:53], v[208:209] op_sel_hi:[1,0]
	v_pk_mul_f32 v[50:51], v[50:51], v[208:209] op_sel_hi:[1,0]
	v_pk_mul_f32 v[48:49], v[48:49], v[208:209] op_sel_hi:[1,0]
	v_pk_mul_f32 v[46:47], v[46:47], v[208:209] op_sel_hi:[1,0]
	v_pk_mul_f32 v[44:45], v[44:45], v[208:209] op_sel_hi:[1,0]
	v_pk_mul_f32 v[42:43], v[42:43], v[208:209] op_sel_hi:[1,0]
	v_pk_mul_f32 v[40:41], v[40:41], v[208:209] op_sel_hi:[1,0]
	v_pk_mul_f32 v[38:39], v[38:39], v[208:209] op_sel_hi:[1,0]
	v_pk_mul_f32 v[36:37], v[36:37], v[208:209] op_sel_hi:[1,0]
	v_pk_mul_f32 v[34:35], v[34:35], v[208:209] op_sel_hi:[1,0]
	v_mov_b32_e32 v208, v221
; __device__ __forceinline__ unsigned cvt_pk_bf16(float lo, float hi) { const f32v2_t v = {lo, hi}; const bf16v2_t r = __builtin_convertvector(v, bf16v2_t); return __builtin_bit_cast(unsigned, r); }
; __device__ __forceinline__ f32x16 mfma32(bf16x8 a, bf16x8 b, f32x16 c) { return __builtin_amdgcn_mfma_f32_32x32x16_bf16(a, b, c, 0, 0, 0); }
; __device__ __forceinline__ void na_item(const bf16_t* __restrict__ proj, const bf16_t* __restrict__ projT, bf16_t* aout, const float* __restrict__ relb  , int item, int seqlen, LAS unsigned char* lds, int w, int lane) {
;     ...
;         for (int qh = 0; qh < 2; ++qh) {
;             f32x16 x = zero16();
; #pragma unroll
;             for (int s = 0; s < 4; ++s) x = mfma32(cur.k[s], qf[qh][s], x);
;             const int qc = 32 * qh + c; float mt = -1e30f;
; #pragma unroll
;             for (int rg = 0; rg < 16; ++rg) { const int kc = 32 * chalf + (rg & 3) + 8 * (rg >> 2) + 4 * hh;
;                 const bool valid = (kc >= cs[qh]) && (kc < cs[qh] + 16);
;                 const float sv = fmaf(x[rg], 0.18033688011112042f, bias[brow + kc - qc + 15]) + (valid ? 0.f : -__builtin_inff());
;                 x[rg] = sv; mt = fmaxf(mt, sv); }
;             mt = xhalf_max(mt);
;             if (__builtin_amdgcn_ballot_w64(mt > mrun[qh] + 8.0f) != 0ull) {
;                 const float mnew = fmaxf(mrun[qh], mt), alpha = __builtin_amdgcn_exp2f(mrun[qh] - mnew);
;                 mrun[qh] = mnew; lrun[qh] *= alpha; O[qh][0] *= alpha; O[qh][1] *= alpha; }
;             const float mcur = mrun[qh];
;             float ps = 0.f;
; #pragma unroll
;             for (int rg = 0; rg < 16; ++rg) { const float p = __builtin_amdgcn_exp2f(x[rg] - mcur); x[rg] = p; ps += p; }
;             lrun[qh] += ps;
; #pragma unroll
;             for (int s2 = 0; s2 < 2; ++s2) {
;                 u32x4 pw; pw.x = cvt_pk_bf16(x[8 * s2 + 0], x[8 * s2 + 1]); pw.y = cvt_pk_bf16(x[8 * s2 + 2], x[8 * s2 + 3]); pw.z = cvt_pk_bf16(x[8 * s2 + 4], x[8 * s2 + 5]); pw.w = cvt_pk_bf16(x[8 * s2 + 6], x[8 * s2 + 7]);
;                 const bf16x8 pb = __builtin_bit_cast(bf16x8, pw);
; #pragma unroll
;                 for (int dt = 0; dt < 2; ++dt) { u32x4 aw; aw.x = cur.v[dt][s2][0].x; aw.y = cur.v[dt][s2][0].y; aw.z = cur.v[dt][s2][1].x; aw.w = cur.v[dt][s2][1].y;
;                     O[qh][dt] = mfma32(__builtin_bit_cast(bf16x8, aw), pb, O[qh][dt]); } }
.LBB0_356:
	v_sub_f32_e32 v66, v66, v208
	v_exp_f32_e32 v221, v66
	v_sub_f32_e32 v66, v67, v208
	v_exp_f32_e32 v222, v66
	v_sub_f32_e32 v66, v68, v208
	v_exp_f32_e32 v223, v66
	v_sub_f32_e32 v66, v69, v208
	v_exp_f32_e32 v224, v66
	v_sub_f32_e32 v66, v70, v208
	v_exp_f32_e32 v225, v66
	v_sub_f32_e32 v66, v71, v208
	v_exp_f32_e32 v227, v66
	v_sub_f32_e32 v66, v72, v208
	v_exp_f32_e32 v230, v66
	v_sub_f32_e32 v66, v73, v208
	v_exp_f32_e32 v233, v66
	v_sub_f32_e32 v66, v74, v208
	v_exp_f32_e32 v235, v66
	v_sub_f32_e32 v66, v75, v208
	v_exp_f32_e32 v247, v66
	v_sub_f32_e32 v66, v76, v208
	v_exp_f32_e32 v249, v66
	v_sub_f32_e32 v66, v77, v208
	v_exp_f32_e32 v251, v66
	v_sub_f32_e32 v66, v78, v208
	v_exp_f32_e32 v252, v66
	v_sub_f32_e32 v66, v79, v208
	v_exp_f32_e32 v253, v66
	v_sub_f32_e32 v66, v80, v208
	v_exp_f32_e32 v248, v66
	v_sub_f32_e32 v66, v81, v208
	v_exp_f32_e32 v250, v66
	v_cvt_pk_bf16_f32 v66, v221, v222
	v_cvt_pk_bf16_f32 v67, v223, v224
	v_cvt_pk_bf16_f32 v68, v225, v227
	v_cvt_pk_bf16_f32 v69, v230, v233
	s_nop 1
	v_mfma_f32_32x32x16_bf16 v[50:65], v[126:129], v[66:69], v[50:65]
	v_mfma_f32_32x32x16_bf16 v[34:49], v[122:125], v[66:69], v[34:49]
	v_cvt_pk_bf16_f32 v66, v235, v247
	v_cvt_pk_bf16_f32 v67, v249, v251
	v_cvt_pk_bf16_f32 v68, v252, v253
	v_cvt_pk_bf16_f32 v69, v248, v250
	s_nop 1
	v_mfma_f32_32x32x16_bf16 v[50:65], v[118:121], v[66:69], v[50:65]
	v_mfma_f32_32x32x16_bf16 v[34:49], v[114:117], v[66:69], v[34:49]
	v_mfma_f32_32x32x16_bf16 v[66:81], v[158:161], v[98:101], 0
	v_mfma_f32_32x32x16_bf16 v[66:81], v[154:157], v[102:105], v[66:81]
	v_mfma_f32_32x32x16_bf16 v[66:81], v[150:153], v[106:109], v[66:81]
	v_mfma_f32_32x32x16_bf16 v[66:81], v[146:149], v[110:113], v[66:81]
	v_sub_u32_e32 v210, s10, v193
	v_lshlrev_b32_e32 v210, 2, v210
	v_add3_u32 v219, s27, v210, v209
	v_add_u32_e32 v219, 0x4a0, v219
	ds_read2_b32 v[146:147], v219 offset1:1
	ds_read2_b32 v[148:149], v219 offset0:2 offset1:3
	ds_read2_b32 v[150:151], v219 offset0:4 offset1:5
	ds_read2_b32 v[152:153], v219 offset0:6 offset1:7
	ds_read2_b32 v[154:155], v219 offset0:16 offset1:17
	ds_read2_b32 v[156:157], v219 offset0:18 offset1:19
	ds_read2_b32 v[158:159], v219 offset0:20 offset1:21
	ds_read2_b32 v[160:161], v219 offset0:22 offset1:23
	v_sub_u32_e32 v218, v0, v195
	s_waitcnt lgkmcnt(0)
	s_nop 1
	v_fmac_f32_e32 v146, 0x3e38aa3b, v66
	v_fmac_f32_e32 v147, 0x3e38aa3b, v67
	v_fmac_f32_e32 v148, 0x3e38aa3b, v68
	v_fmac_f32_e32 v149, 0x3e38aa3b, v69
	v_fmac_f32_e32 v150, 0x3e38aa3b, v70
	v_fmac_f32_e32 v151, 0x3e38aa3b, v71
	v_fmac_f32_e32 v152, 0x3e38aa3b, v72
	v_fmac_f32_e32 v153, 0x3e38aa3b, v73
	v_fmac_f32_e32 v154, 0x3e38aa3b, v74
	v_fmac_f32_e32 v155, 0x3e38aa3b, v75
	v_fmac_f32_e32 v156, 0x3e38aa3b, v76
	v_fmac_f32_e32 v157, 0x3e38aa3b, v77
	v_fmac_f32_e32 v158, 0x3e38aa3b, v78
	v_fmac_f32_e32 v159, 0x3e38aa3b, v79
	v_fmac_f32_e32 v160, 0x3e38aa3b, v80
	v_fmac_f32_e32 v161, 0x3e38aa3b, v81
	v_add_u32_e32 v212, 1, v218
	v_add_u32_e32 v213, 2, v218
	v_add_u32_e32 v214, 3, v218
	v_cmp_gt_u32_e32 vcc, 16, v218
	v_cmp_gt_u32_e64 s[0:1], 16, v212
	v_cmp_gt_u32_e64 s[38:39], 16, v213
	v_cmp_gt_u32_e64 s[40:41], 16, v214
	v_cndmask_b32_e32 v146, v241, v146, vcc
	v_cndmask_b32_e64 v66, v241, v147, s[0:1]
	v_cndmask_b32_e64 v67, v241, v148, s[38:39]
	v_cndmask_b32_e64 v68, v241, v149, s[40:41]
	v_add_u32_e32 v211, 4, v218
	v_add_u32_e32 v212, 5, v218
	v_add_u32_e32 v213, 6, v218
	v_add_u32_e32 v214, 7, v218
	v_cmp_gt_u32_e32 vcc, 16, v211
	v_cmp_gt_u32_e64 s[0:1], 16, v212
	v_cmp_gt_u32_e64 s[38:39], 16, v213
	v_cmp_gt_u32_e64 s[40:41], 16, v214
	v_cndmask_b32_e32 v0, v241, v150, vcc
	v_cndmask_b32_e64 v69, v241, v151, s[0:1]
	v_cndmask_b32_e64 v70, v241, v152, s[38:39]
	v_cndmask_b32_e64 v71, v241, v153, s[40:41]
	v_add_u32_e32 v211, 16, v218
	v_add_u32_e32 v212, 17, v218
	v_add_u32_e32 v213, 18, v218
	v_add_u32_e32 v214, 19, v218
	v_cmp_gt_u32_e32 vcc, 16, v211
	v_cmp_gt_u32_e64 s[0:1], 16, v212
	v_cmp_gt_u32_e64 s[38:39], 16, v213
	v_cmp_gt_u32_e64 s[40:41], 16, v214
	v_cndmask_b32_e32 v72, v241, v154, vcc
	v_cndmask_b32_e64 v73, v241, v155, s[0:1]
	v_cndmask_b32_e64 v74, v241, v156, s[38:39]
	v_cndmask_b32_e64 v75, v241, v157, s[40:41]
	v_add_u32_e32 v211, 20, v218
	v_add_u32_e32 v212, 21, v218
	v_add_u32_e32 v213, 22, v218
	v_add_u32_e32 v214, 23, v218
	v_cmp_gt_u32_e32 vcc, 16, v211
	v_cmp_gt_u32_e64 s[0:1], 16, v212
	v_cmp_gt_u32_e64 s[38:39], 16, v213
	v_cmp_gt_u32_e64 s[40:41], 16, v214
	v_cndmask_b32_e32 v77, v241, v158, vcc
	v_cndmask_b32_e64 v76, v241, v159, s[0:1]
	v_cndmask_b32_e64 v78, v241, v160, s[38:39]
	v_cndmask_b32_e64 v79, v241, v161, s[40:41]
	v_max3_f32 v210, v146, s19, v66
	v_max3_f32 v210, v210, v67, v68
	v_max3_f32 v210, v210, v0, v69
	v_max3_f32 v210, v210, v70, v71
	v_max3_f32 v210, v210, v72, v73
	v_max3_f32 v210, v210, v74, v75
	v_max3_f32 v210, v210, v77, v76
	v_max3_f32 v80, v210, v78, v79
	v_mov_b32_e32 v81, v80
	s_nop 1
	v_permlane32_swap_b32_e32 v80, v81
	v_max_f32_e32 v81, v81, v81
	v_max_f32_e32 v80, v80, v80
	v_max_f32_e32 v80, v80, v81
	v_add_f32_e32 v81, 0x41000000, v207
	v_cmp_gt_f32_e32 vcc, v80, v81
	s_cbranch_vccz .LBB0_358
	v_max_f32_e32 v80, v80, v80
	v_max_f32_e32 v81, v207, v207
	v_max_f32_e32 v81, v81, v80
	v_sub_f32_e32 v80, v207, v81
	v_exp_f32_e32 v80, v80
	v_mov_b32_e32 v207, v81
	v_mul_f32_e32 v163, v163, v80
	v_pk_mul_f32 v[32:33], v[32:33], v[80:81] op_sel_hi:[1,0]
	v_pk_mul_f32 v[30:31], v[30:31], v[80:81] op_sel_hi:[1,0]
	v_pk_mul_f32 v[28:29], v[28:29], v[80:81] op_sel_hi:[1,0]
	v_pk_mul_f32 v[26:27], v[26:27], v[80:81] op_sel_hi:[1,0]
	v_pk_mul_f32 v[24:25], v[24:25], v[80:81] op_sel_hi:[1,0]
	v_pk_mul_f32 v[22:23], v[22:23], v[80:81] op_sel_hi:[1,0]
	v_pk_mul_f32 v[20:21], v[20:21], v[80:81] op_sel_hi:[1,0]
	v_pk_mul_f32 v[18:19], v[18:19], v[80:81] op_sel_hi:[1,0]
	v_pk_mul_f32 v[16:17], v[16:17], v[80:81] op_sel_hi:[1,0]
	v_pk_mul_f32 v[14:15], v[14:15], v[80:81] op_sel_hi:[1,0]
	v_pk_mul_f32 v[12:13], v[12:13], v[80:81] op_sel_hi:[1,0]
	v_pk_mul_f32 v[10:11], v[10:11], v[80:81] op_sel_hi:[1,0]
	v_pk_mul_f32 v[8:9], v[8:9], v[80:81] op_sel_hi:[1,0]
	v_pk_mul_f32 v[6:7], v[6:7], v[80:81] op_sel_hi:[1,0]
	v_pk_mul_f32 v[4:5], v[4:5], v[80:81] op_sel_hi:[1,0]
	v_pk_mul_f32 v[2:3], v[2:3], v[80:81] op_sel_hi:[1,0]
